# PH5 queue tail: one dequeue covers two layer-1 weight-copy items per wave (256 dequeues instead of 512)
# speedup vs baseline: 1.0009x; 1.0009x over previous
.LBB0_1844:
	s_or_b64 exec, exec, s[4:5]
	s_waitcnt lgkmcnt(0)
	s_barrier
	ds_read_b32 v0, v196
	s_mov_b64 s[4:5], -1
	s_waitcnt lgkmcnt(0)
	s_barrier
	v_readfirstlane_b32 s34, v0
	s_mov_b32 s99, 1
	s_cmpk_gt_i32 s34, 0x2ff
	s_cbranch_scc1 .LBB0_1839
	s_cmpk_lt_i32 s34, 0x100
	s_cselect_b64 s[4:5], -1, 0
	s_cmpk_gt_i32 s34, 0xff
	s_cselect_b64 s[6:7], -1, 0
	s_mov_b32 s8, 0
	s_and_b64 vcc, exec, s[4:5]
	s_cbranch_vccnz .LBB0_1848
	s_cmpk_lt_u32 s34, 0x180
	s_mov_b32 s8, 1
	s_cbranch_scc1 .LBB0_1848
	s_cmpk_lt_u32 s34, 0x200
	s_cselect_b32 s8, 3, 4
	s_cmpk_gt_u32 s34, 0x1bf
	s_cselect_b32 s8, s8, 2

.LBB0_1904:
	s_and_b64 vcc, exec, s[4:5]
	s_cbranch_vccz .LBB0_1906
	s_mov_b32 s100, 0
.Lw5_again:
	v_readlane_b32 s4, v254, 35
	s_add_i32 s8, s4, s44
	s_cmpk_lt_u32 s8, 0x20a0
	s_cselect_b64 s[4:5], -1, 0
	s_and_b64 s[10:11], s[4:5], exec
	s_movk_i32 s10, 0xe760
	s_cselect_b32 s10, s10, 0xffffdf60
	s_mov_b32 s11, 0x1b00000
	s_cselect_b32 s16, s41, s43
	s_cselect_b32 s17, s40, s42
	s_cselect_b32 s11, s11, 0x2300000
	s_add_i32 s8, s8, s10
	s_add_u32 s10, s50, s11
	s_addc_u32 s11, s51, 0
	s_and_b64 s[12:13], s[4:5], exec
	s_cselect_b32 s12, 7, 5
	s_lshr_b32 s12, s8, s12
	s_and_b64 s[14:15], s[4:5], exec
	s_cselect_b32 s13, 0x7f, 31
	s_and_b32 s8, s8, s13
	s_lshl_b32 s13, s8, 7
	v_ashrrev_i32_e32 v2, 3, v199
	s_add_u32 s14, s17, s13
	v_lshlrev_b32_e32 v1, 4, v199
	v_lshl_add_u32 v0, s12, 6, v2
	s_addc_u32 s15, s16, 0
	v_and_b32_e32 v160, 0x70, v1
	v_lshl_add_u64 v[32:33], s[14:15], 0, v[160:161]
	s_and_b64 s[14:15], s[4:5], exec
	v_add_u32_e32 v8, 8, v0
	v_ashrrev_i32_e32 v1, 31, v0
	s_cselect_b32 s13, 12, 10
	v_ashrrev_i32_e32 v9, 31, v8
	v_lshlrev_b64 v[4:5], s13, v[0:1]
	v_lshlrev_b64 v[8:9], s13, v[8:9]
	v_add_u32_e32 v12, 16, v0
	v_lshl_add_u64 v[4:5], v[4:5], 2, v[32:33]
	v_lshl_add_u64 v[8:9], v[8:9], 2, v[32:33]
	v_ashrrev_i32_e32 v13, 31, v12
	global_load_dwordx4 v[4:7], v[4:5], off
	v_lshlrev_b64 v[12:13], s13, v[12:13]
	global_load_dwordx4 v[8:11], v[8:9], off
	v_add_u32_e32 v16, 24, v0
	v_lshl_add_u64 v[12:13], v[12:13], 2, v[32:33]
	v_ashrrev_i32_e32 v17, 31, v16
	global_load_dwordx4 v[12:15], v[12:13], off
	v_lshlrev_b64 v[16:17], s13, v[16:17]
	v_add_u32_e32 v20, 32, v0
	v_lshl_add_u64 v[16:17], v[16:17], 2, v[32:33]
	v_ashrrev_i32_e32 v21, 31, v20
	global_load_dwordx4 v[16:19], v[16:17], off
	v_lshlrev_b64 v[20:21], s13, v[20:21]
	v_add_u32_e32 v24, 40, v0
	v_lshl_add_u64 v[20:21], v[20:21], 2, v[32:33]
	v_ashrrev_i32_e32 v25, 31, v24
	global_load_dwordx4 v[20:23], v[20:21], off
	v_lshlrev_b64 v[24:25], s13, v[24:25]
	v_add_u32_e32 v28, 48, v0
	v_lshl_add_u64 v[24:25], v[24:25], 2, v[32:33]
	v_ashrrev_i32_e32 v29, 31, v28
	global_load_dwordx4 v[24:27], v[24:25], off
	v_lshlrev_b64 v[28:29], s13, v[28:29]
	v_add_u32_e32 v0, 56, v0
	v_lshl_add_u64 v[28:29], v[28:29], 2, v[32:33]
	v_ashrrev_i32_e32 v1, 31, v0
	global_load_dwordx4 v[28:31], v[28:29], off
	v_lshlrev_b64 v[0:1], s13, v[0:1]
	v_lshl_add_u64 v[0:1], v[0:1], 2, v[32:33]
	global_load_dwordx4 v[32:35], v[0:1], off
	s_movk_i32 s13, 0x84
	v_mul_lo_u32 v0, v2, s13
	v_add3_u32 v0, s69, v160, v0
	v_add_u32_e32 v1, 0x420, v0
	s_lshl_b32 s12, s12, 7
	s_add_u32 s10, s10, s12
	s_addc_u32 s11, s11, 0
	s_and_b64 s[4:5], s[4:5], exec
	s_cselect_b32 s4, 10, 12
	s_waitcnt vmcnt(7)
	ds_write2_b32 v0, v4, v5 offset1:1
	ds_write2_b32 v0, v6, v7 offset0:2 offset1:3
	v_lshlrev_b32_e32 v4, 2, v2
	s_waitcnt vmcnt(6)
	ds_write2_b32 v1, v8, v9 offset1:1
	v_add_u32_e32 v1, 0x428, v0
	ds_write2_b32 v1, v10, v11 offset1:1
	v_add_u32_e32 v1, 0x840, v0
	s_waitcnt vmcnt(5)
	ds_write2_b32 v1, v12, v13 offset1:1
	v_add_u32_e32 v1, 0x848, v0
	ds_write2_b32 v1, v14, v15 offset1:1
	v_add_u32_e32 v1, 0xc60, v0
	s_waitcnt vmcnt(4)
	ds_write2_b32 v1, v16, v17 offset1:1
	v_add_u32_e32 v1, 0xc68, v0
	ds_write2_b32 v1, v18, v19 offset1:1
	v_add_u32_e32 v1, 0x1080, v0
	s_waitcnt vmcnt(3)
	ds_write2_b32 v1, v20, v21 offset1:1
	v_add_u32_e32 v1, 0x1088, v0
	ds_write2_b32 v1, v22, v23 offset1:1
	v_add_u32_e32 v1, 0x14a0, v0
	s_waitcnt vmcnt(2)
	ds_write2_b32 v1, v24, v25 offset1:1
	v_add_u32_e32 v1, 0x14a8, v0
	ds_write2_b32 v1, v26, v27 offset1:1
	v_add_u32_e32 v1, 0x18c0, v0
	v_lshl_add_u32 v24, s8, 5, v2
	s_waitcnt vmcnt(1)
	ds_write2_b32 v1, v28, v29 offset1:1
	v_add_u32_e32 v1, 0x18c8, v0
	ds_write2_b32 v1, v30, v31 offset1:1
	v_add_u32_e32 v1, 0x1ce0, v0
	v_add_u32_e32 v0, 0x1ce8, v0
	s_waitcnt vmcnt(0)
	ds_write2_b32 v0, v34, v35 offset1:1
	v_lshlrev_b32_e32 v0, 3, v199
	ds_write2_b32 v1, v32, v33 offset1:1
	v_and_b32_e32 v0, 56, v0
	s_waitcnt lgkmcnt(0)
	v_mul_u32_u24_e32 v3, 0x84, v0
	v_add3_u32 v26, s69, v3, v4
	ds_read2_b32 v[8:9], v26 offset0:33 offset1:41
	ds_read2_b32 v[10:11], v26 offset1:8
	ds_read2_b32 v[12:13], v26 offset0:66 offset1:74
	ds_read2_b32 v[14:15], v26 offset0:99 offset1:107
	ds_read2_b32 v[16:17], v26 offset0:132 offset1:140
	ds_read2_b32 v[18:19], v26 offset0:165 offset1:173
	ds_read2_b32 v[20:21], v26 offset0:198 offset1:206
	ds_read2_b32 v[22:23], v26 offset0:231 offset1:239
	s_waitcnt lgkmcnt(7)
	v_bfe_u32 v4, v8, 16, 1
	s_waitcnt lgkmcnt(6)
	v_bfe_u32 v3, v10, 16, 1
	v_add3_u32 v3, v10, v3, s93
	v_lshrrev_b32_e32 v3, 16, v3
	v_add3_u32 v4, v8, v4, s93
	v_and_or_b32 v4, v4, s95, v3
	s_waitcnt lgkmcnt(5)
	v_bfe_u32 v3, v12, 16, 1
	v_add3_u32 v3, v12, v3, s93
	s_waitcnt lgkmcnt(4)
	v_bfe_u32 v5, v14, 16, 1
	v_lshrrev_b32_e32 v3, 16, v3
	v_add3_u32 v5, v14, v5, s93
	v_and_or_b32 v5, v5, s95, v3
	s_waitcnt lgkmcnt(3)
	v_bfe_u32 v3, v16, 16, 1
	v_add3_u32 v3, v16, v3, s93
	s_waitcnt lgkmcnt(2)
	v_bfe_u32 v6, v18, 16, 1
	v_lshrrev_b32_e32 v3, 16, v3
	v_add3_u32 v6, v18, v6, s93
	v_and_or_b32 v6, v6, s95, v3
	s_waitcnt lgkmcnt(1)
	v_bfe_u32 v3, v20, 16, 1
	v_add3_u32 v3, v20, v3, s93
	s_waitcnt lgkmcnt(0)
	v_bfe_u32 v7, v22, 16, 1
	v_lshlrev_b32_e32 v160, 1, v0
	v_lshrrev_b32_e32 v3, 16, v3
	v_add3_u32 v7, v22, v7, s93
	v_ashrrev_i32_e32 v25, 31, v24
	v_lshl_add_u64 v[0:1], s[10:11], 0, v[160:161]
	v_and_or_b32 v7, v7, s95, v3
	v_lshlrev_b64 v[2:3], s4, v[24:25]
	v_lshl_add_u64 v[2:3], v[2:3], 1, v[0:1]
	global_store_dwordx4 v[2:3], v[4:7], off
	v_bfe_u32 v2, v11, 16, 1
	v_add3_u32 v2, v11, v2, s93
	v_bfe_u32 v3, v9, 16, 1
	v_lshrrev_b32_e32 v2, 16, v2
	v_add3_u32 v3, v9, v3, s93
	v_and_or_b32 v2, v3, s95, v2
	v_bfe_u32 v3, v13, 16, 1
	v_add3_u32 v3, v13, v3, s93
	v_bfe_u32 v4, v15, 16, 1
	v_lshrrev_b32_e32 v3, 16, v3
	v_add3_u32 v4, v15, v4, s93
	v_and_or_b32 v3, v4, s95, v3
	v_bfe_u32 v4, v17, 16, 1
	v_add3_u32 v4, v17, v4, s93
	v_bfe_u32 v5, v19, 16, 1
	v_lshrrev_b32_e32 v4, 16, v4
	v_add3_u32 v5, v19, v5, s93
	v_and_or_b32 v4, v5, s95, v4
	v_bfe_u32 v5, v21, 16, 1
	v_add3_u32 v5, v21, v5, s93
	v_bfe_u32 v6, v23, 16, 1
	v_lshrrev_b32_e32 v5, 16, v5
	v_add3_u32 v6, v23, v6, s93
	v_and_or_b32 v5, v6, s95, v5
	v_add_u32_e32 v6, 8, v24
	v_ashrrev_i32_e32 v7, 31, v6
	v_lshlrev_b64 v[6:7], s4, v[6:7]
	v_lshl_add_u64 v[6:7], v[6:7], 1, v[0:1]
	global_store_dwordx4 v[6:7], v[2:5], off
	ds_read2_b32 v[6:7], v26 offset0:16 offset1:24
	ds_read2_b32 v[8:9], v26 offset0:49 offset1:57
	ds_read2_b32 v[10:11], v26 offset0:82 offset1:90
	ds_read2_b32 v[12:13], v26 offset0:115 offset1:123
	ds_read2_b32 v[14:15], v26 offset0:148 offset1:156
	ds_read2_b32 v[16:17], v26 offset0:181 offset1:189
	ds_read2_b32 v[18:19], v26 offset0:214 offset1:222
	ds_read2_b32 v[20:21], v26 offset0:247 offset1:255
	s_waitcnt lgkmcnt(7)
	v_bfe_u32 v2, v6, 16, 1
	v_add3_u32 v2, v6, v2, s93
	s_waitcnt lgkmcnt(6)
	v_bfe_u32 v3, v8, 16, 1
	v_lshrrev_b32_e32 v2, 16, v2
	v_add3_u32 v3, v8, v3, s93
	v_and_or_b32 v2, v3, s95, v2
	s_waitcnt lgkmcnt(5)
	v_bfe_u32 v3, v10, 16, 1
	v_add3_u32 v3, v10, v3, s93
	s_waitcnt lgkmcnt(4)
	v_bfe_u32 v4, v12, 16, 1
	v_lshrrev_b32_e32 v3, 16, v3
	v_add3_u32 v4, v12, v4, s93
	v_and_or_b32 v3, v4, s95, v3
	s_waitcnt lgkmcnt(3)
	v_bfe_u32 v4, v14, 16, 1
	v_add3_u32 v4, v14, v4, s93
	s_waitcnt lgkmcnt(2)
	v_bfe_u32 v5, v16, 16, 1
	v_lshrrev_b32_e32 v4, 16, v4
	v_add3_u32 v5, v16, v5, s93
	v_and_or_b32 v4, v5, s95, v4
	s_waitcnt lgkmcnt(1)
	v_bfe_u32 v5, v18, 16, 1
	v_add_u32_e32 v22, 16, v24
	v_add3_u32 v5, v18, v5, s93
	s_waitcnt lgkmcnt(0)
	v_bfe_u32 v6, v20, 16, 1
	v_ashrrev_i32_e32 v23, 31, v22
	v_lshrrev_b32_e32 v5, 16, v5
	v_add3_u32 v6, v20, v6, s93
	v_lshlrev_b64 v[22:23], s4, v[22:23]
	v_and_or_b32 v5, v6, s95, v5
	v_lshl_add_u64 v[22:23], v[22:23], 1, v[0:1]
	global_store_dwordx4 v[22:23], v[2:5], off
	v_bfe_u32 v6, v21, 16, 1
	v_add3_u32 v6, v21, v6, s93
	v_bfe_u32 v2, v7, 16, 1
	v_add3_u32 v2, v7, v2, s93
	v_bfe_u32 v3, v9, 16, 1
	v_lshrrev_b32_e32 v2, 16, v2
	v_add3_u32 v3, v9, v3, s93
	v_and_or_b32 v2, v3, s95, v2
	v_bfe_u32 v3, v11, 16, 1
	v_add3_u32 v3, v11, v3, s93
	v_bfe_u32 v4, v13, 16, 1
	v_lshrrev_b32_e32 v3, 16, v3
	v_add3_u32 v4, v13, v4, s93
	v_and_or_b32 v3, v4, s95, v3
	v_bfe_u32 v4, v15, 16, 1
	v_add3_u32 v4, v15, v4, s93
	v_bfe_u32 v5, v17, 16, 1
	v_lshrrev_b32_e32 v4, 16, v4
	v_add3_u32 v5, v17, v5, s93
	v_and_or_b32 v4, v5, s95, v4
	v_bfe_u32 v5, v19, 16, 1
	v_add3_u32 v5, v19, v5, s93
	v_lshrrev_b32_e32 v5, 16, v5
	v_and_or_b32 v5, v6, s95, v5
	v_add_u32_e32 v6, 24, v24
	v_ashrrev_i32_e32 v7, 31, v6
	v_lshlrev_b64 v[6:7], s4, v[6:7]
	v_lshl_add_u64 v[0:1], v[6:7], 1, v[0:1]
	global_store_dwordx4 v[0:1], v[2:5], off
	s_waitcnt lgkmcnt(0)
	s_addk_i32 s44, 0x800
	s_add_i32 s100, s100, 1
	s_cmp_lt_u32 s100, 2
	s_cbranch_scc1 .Lw5_again
	s_barrier
